# work removal stack on pack_more: folded landed-flag control flow in 3 K-loops + no redundant As[1][1] re-stage on fresh units
# baseline (speedup 1.0000x reference)
; #define PG8_STAGE(bufoff, gbase, voff) glds16s2((voff)[0], (voff)[1], (const void*)(gbase), ldsn + (unsigned)(bufoff))
; #define PG8_LDA(dst, b, h) do { _Pragma("unroll") for (int m = 0; m < 4; ++m) _Pragma("unroll") for (int k = 0; k < 2; ++k) dst[m][k] = *(const LAS bf16x8*)(lds + PG8_SA(b, h) + aoff + m * 2048 + k * 1024); } while (0)
; #define PG8_LDB(dst, b, h) do { _Pragma("unroll") for (int n = 0; n < 2; ++n) _Pragma("unroll") for (int k = 0; k < 2; ++k) dst[n][k] = *(const LAS bf16x8*)(lds + PG8_SB(b, h) + boff + n * 2048 + k * 1024); } while (0)
; #define PG8_WAIT_V(n) asm volatile("s_waitcnt vmcnt(" #n ")" ::: "memory")
; #define PG8_SCHED __builtin_amdgcn_sched_barrier(0)
; template <class Epi, bool ALIGN_EPI, bool EARLY_DRAIN = true, class Pre = NoPre>
; __device__ __forceinline__ void gemm_phase(LAS unsigned char* lds, const Gemm g, const StaticOrder& S, const Epi& E, int wv, const Pre& pre = Pre()) {
;     ...
;             int lf_ = EARLY_DRAIN ? __builtin_amdgcn_readfirstlane(landed_flag) : landed_flag; if constexpr (EARLY_DRAIN) asm volatile("" : "+s"(lf_)); landed_flag = 0;
;             PG8_LDB(B0, 0, 0); PG8_LDB(B1, 0, 1); PG8_SCHED; PG8_LDA(At, 0, 0); PG8_STAGE(PG8_SA(1, 1), a1 + ahs, voffA);
;             if (!lf_) PG8_WAIT_V(8);
.LBB0_170:
	v_cndmask_b32_e64 v2, 0, 1, s[84:85]
	v_add_u32_e32 v245, 0x10000, v233
	v_readfirstlane_b32 s0, v2
	s_and_b32 s0, s0, 1
	v_add_u32_e32 v246, 0x14000, v233
	s_waitcnt lgkmcnt(14)
	ds_read_b128 v[86:89], v245
	ds_read_b128 v[90:93], v245 offset:1024
	ds_read_b128 v[94:97], v245 offset:2048
	ds_read_b128 v[98:101], v245 offset:3072
	s_waitcnt lgkmcnt(13)
	ds_read_b128 v[50:53], v246
	s_waitcnt lgkmcnt(11)
	ds_read_b128 v[62:65], v246 offset:1024
	ds_read_b128 v[70:73], v246 offset:2048
	ds_read_b128 v[82:85], v246 offset:3072
	s_waitcnt lgkmcnt(13)
	ds_read_b128 v[38:41], v244
	s_waitcnt lgkmcnt(11)
	ds_read_b128 v[42:45], v244 offset:1024
	ds_read_b128 v[46:49], v244 offset:2048
	ds_read_b128 v[54:57], v244 offset:3072
	ds_read_b128 v[58:61], v244 offset:4096
	ds_read_b128 v[66:69], v244 offset:5120
	ds_read_b128 v[74:77], v244 offset:6144
	ds_read_b128 v[78:81], v244 offset:7168
	s_add_u32 s38, s70, 0x40080
	s_addc_u32 s39, s71, 0
	s_cmp_lg_u32 s0, 0
	s_cbranch_scc1 .Lfresh_skip_a11_2
	s_mov_b32 m0, s26
	s_nop 0
	global_load_lds_dwordx4 v0, s[38:39]
	s_add_u32 m0, m0, 0x2000
	s_nop 0
	global_load_lds_dwordx4 v231, s[38:39]
.Lfresh_skip_a11_2:
	s_cmp_eq_u32 s0, 0
	s_cselect_b64 s[84:85], -1, 0
	s_cmp_lg_u32 s0, 0
	s_cbranch_scc1 .LBB0_172
	s_waitcnt vmcnt(8)

; #define PG8_STAGE(bufoff, gbase, voff) glds16s2((voff)[0], (voff)[1], (const void*)(gbase), ldsn + (unsigned)(bufoff))
; #define PG8_LDA(dst, b, h) do { _Pragma("unroll") for (int m = 0; m < 4; ++m) _Pragma("unroll") for (int k = 0; k < 2; ++k) dst[m][k] = *(const LAS bf16x8*)(lds + PG8_SA(b, h) + aoff + m * 2048 + k * 1024); } while (0)
; #define PG8_LDB(dst, b, h) do { _Pragma("unroll") for (int n = 0; n < 2; ++n) _Pragma("unroll") for (int k = 0; k < 2; ++k) dst[n][k] = *(const LAS bf16x8*)(lds + PG8_SB(b, h) + boff + n * 2048 + k * 1024); } while (0)
; #define PG8_WAIT_V(n) asm volatile("s_waitcnt vmcnt(" #n ")" ::: "memory")
; #define PG8_SCHED __builtin_amdgcn_sched_barrier(0)
; template <class Epi, bool ALIGN_EPI, bool EARLY_DRAIN = true, class Pre = NoPre>
; __device__ __forceinline__ void gemm_phase(LAS unsigned char* lds, const Gemm g, const StaticOrder& S, const Epi& E, int wv, const Pre& pre = Pre()) {
;     ...
;             int lf_ = EARLY_DRAIN ? __builtin_amdgcn_readfirstlane(landed_flag) : landed_flag; if constexpr (EARLY_DRAIN) asm volatile("" : "+s"(lf_)); landed_flag = 0;
;             PG8_LDB(B0, 0, 0); PG8_LDB(B1, 0, 1); PG8_SCHED; PG8_LDA(At, 0, 0); PG8_STAGE(PG8_SA(1, 1), a1 + ahs, voffA);
;             if (!lf_) PG8_WAIT_V(8);
.LBB0_551:
	v_add_u32_e32 v0, 0x10000, v244
	v_add_u32_e32 v234, 0x14000, v244
	s_waitcnt lgkmcnt(12)
	ds_read_b128 v[74:77], v0
	ds_read_b128 v[82:85], v0 offset:1024
	ds_read_b128 v[86:89], v0 offset:2048
	ds_read_b128 v[96:99], v0 offset:3072
	s_waitcnt lgkmcnt(13)
	ds_read_b128 v[50:53], v234
	s_waitcnt lgkmcnt(13)
	ds_read_b128 v[54:57], v234 offset:1024
	ds_read_b128 v[66:69], v234 offset:2048
	ds_read_b128 v[70:73], v234 offset:3072
	s_waitcnt lgkmcnt(13)
	ds_read_b128 v[38:41], v245
	s_waitcnt lgkmcnt(11)
	ds_read_b128 v[42:45], v245 offset:1024
	ds_read_b128 v[46:49], v245 offset:2048
	ds_read_b128 v[58:61], v245 offset:3072
	ds_read_b128 v[62:65], v245 offset:4096
	ds_read_b128 v[78:81], v245 offset:5120
	ds_read_b128 v[90:93], v245 offset:6144
	ds_read_b128 v[100:103], v245 offset:7168
	s_add_u32 s14, s86, 0x2080
	s_addc_u32 s15, s87, 0
	s_cmp_lg_u32 s0, 0
	s_cbranch_scc1 .Lfresh_skip_a11_1
	s_mov_b32 m0, s67
	s_nop 0
	global_load_lds_dwordx4 v250, s[14:15]
	s_add_u32 m0, m0, 0x2000
	s_nop 0
	global_load_lds_dwordx4 v246, s[14:15]
.Lfresh_skip_a11_1:
	s_cmp_eq_u32 s0, 0
	s_cselect_b64 s[88:89], -1, 0
	s_cmp_lg_u32 s0, 0
	s_cbranch_scc1 .LBB0_553
	s_waitcnt vmcnt(8)

; #define PG8_STAGE(bufoff, gbase, voff) glds16s2((voff)[0], (voff)[1], (const void*)(gbase), ldsn + (unsigned)(bufoff))
; #define PG8_LDA(dst, b, h) do { _Pragma("unroll") for (int m = 0; m < 4; ++m) _Pragma("unroll") for (int k = 0; k < 2; ++k) dst[m][k] = *(const LAS bf16x8*)(lds + PG8_SA(b, h) + aoff + m * 2048 + k * 1024); } while (0)
; #define PG8_LDB(dst, b, h) do { _Pragma("unroll") for (int n = 0; n < 2; ++n) _Pragma("unroll") for (int k = 0; k < 2; ++k) dst[n][k] = *(const LAS bf16x8*)(lds + PG8_SB(b, h) + boff + n * 2048 + k * 1024); } while (0)
; #define PG8_SCHED __builtin_amdgcn_sched_barrier(0)
; template <class Epi, bool ALIGN_EPI, bool EARLY_DRAIN = true, class Pre = NoPre>
; __device__ __forceinline__ void gemm_phase(LAS unsigned char* lds, const Gemm g, const StaticOrder& S, const Epi& E, int wv, const Pre& pre = Pre()) {
;     ...
;             int lf_ = EARLY_DRAIN ? __builtin_amdgcn_readfirstlane(landed_flag) : landed_flag; if constexpr (EARLY_DRAIN) asm volatile("" : "+s"(lf_)); landed_flag = 0;
;             PG8_LDB(B0, 0, 0); PG8_LDB(B1, 0, 1); PG8_SCHED; PG8_LDA(At, 0, 0); PG8_STAGE(PG8_SA(1, 1), a1 + ahs, voffA);
.LBB0_727:
	v_add_u32_e32 v234, 0x10000, v233
	v_add_u32_e32 v235, 0x14000, v233
	s_waitcnt lgkmcnt(14)
	ds_read_b128 v[82:85], v234
	ds_read_b128 v[86:89], v234 offset:1024
	ds_read_b128 v[90:93], v234 offset:2048
	ds_read_b128 v[94:97], v234 offset:3072
	s_waitcnt lgkmcnt(14)
	ds_read_b128 v[66:69], v235
	ds_read_b128 v[70:73], v235 offset:1024
	ds_read_b128 v[74:77], v235 offset:2048
	ds_read_b128 v[78:81], v235 offset:3072
	s_waitcnt lgkmcnt(13)
	ds_read_b128 v[38:41], v250
	s_waitcnt lgkmcnt(11)
	ds_read_b128 v[42:45], v250 offset:1024
	ds_read_b128 v[46:49], v250 offset:2048
	ds_read_b128 v[50:53], v250 offset:3072
	ds_read_b128 v[54:57], v250 offset:4096
	ds_read_b128 v[58:61], v250 offset:5120
	ds_read_b128 v[62:65], v250 offset:6144
	ds_read_b128 v[98:101], v250 offset:7168
	s_add_u32 s14, s70, 0xb0080
	s_addc_u32 s15, s71, 0
	s_cmp_lg_u32 s0, 0
	s_cbranch_scc1 .Lfresh_skip_a11_0
	s_mov_b32 m0, s67
	s_nop 0
	global_load_lds_dwordx4 v0, s[14:15]
	s_add_u32 m0, m0, 0x2000
	s_nop 0
	global_load_lds_dwordx4 v231, s[14:15]
